# grid barrier: member workgroups poll the top-level generation word directly (same count as their XCD word) - one hop less between last arrival and release; on top of arrival-time acquire
# speedup vs baseline: 1.0233x; 1.0033x over previous
; DI unsigned xb_ld(unsigned* p) { return __hip_atomic_load(p, __ATOMIC_RELAXED, __HIP_MEMORY_SCOPE_AGENT); }
; DI unsigned xb_add(unsigned* p, unsigned v) { return __hip_atomic_fetch_add(p, v, __ATOMIC_RELAXED, __HIP_MEMORY_SCOPE_AGENT); }
; #define XB_SPIN(cond, bar) do { unsigned _sp = 0; while (cond) { __builtin_amdgcn_s_sleep(1); \
;     if ((++_sp & 255u) == 0u) { if (xb_ld(&(bar)[XB_TMO])) break; if (_sp > XB_SPIN_CAP) { atomicAdd(&(bar)[XB_TMO], 1u); break; } } } } while (0)
; DI void xcd_barrier(const XcdBarrier& b) {
;     ...
;     const unsigned old = xb_add(&bar[XB_XSUB(b.x)], 1u);
;     const unsigned gen = old / nloc;
;     if (old + 1u == (gen + 1u) * nloc) {
;       __builtin_amdgcn_fence(__ATOMIC_RELEASE, "agent");
;       asm volatile("s_waitcnt vmcnt(0)" ::: "memory");
;       const unsigned og = xb_add(&bar[XB_TOP], 1u);
;       const unsigned tg = og / nx;
;       if (og + 1u == (tg + 1u) * nx) xb_add(&bar[XB_TOPGEN], 1u);
;       else XB_SPIN(xb_ld(&bar[XB_TOPGEN]) == tg, bar);
;       __builtin_amdgcn_fence(__ATOMIC_ACQUIRE, "agent");
;       xb_add(&bar[XB_XGEN(b.x)], 1u);
;       asm volatile("s_waitcnt vmcnt(0)" ::: "memory");
;     } else {
;       XB_SPIN(xb_ld(&bar[XB_XGEN(b.x)]) == gen, bar);
;       __builtin_amdgcn_fence(__ATOMIC_ACQUIRE, "agent");
.LBB0_279:
	s_or_b64 exec, exec, s[14:15]
	v_cvt_f32_u32_e32 v6, v4
	s_waitcnt vmcnt(0)
	v_readfirstlane_b32 s2, v5
	v_sub_u32_e32 v5, 0, v4
	v_rcp_iflag_f32_e32 v6, v6
	v_add_u32_e32 v7, s2, v3
	v_mul_f32_e32 v6, 0x4f7ffffe, v6
	v_cvt_u32_f32_e32 v6, v6
	v_mul_lo_u32 v3, v5, v6
	v_mul_hi_u32 v3, v6, v3
	v_add_u32_e32 v3, v6, v3
	v_mul_hi_u32 v3, v7, v3
	v_mul_lo_u32 v5, v3, v4
	v_sub_u32_e32 v5, v7, v5
	v_add_u32_e32 v6, 1, v3
	v_cmp_ge_u32_e32 vcc, v5, v4
	s_nop 1
	v_cndmask_b32_e32 v3, v3, v6, vcc
	v_sub_u32_e32 v6, v5, v4
	v_cndmask_b32_e32 v5, v5, v6, vcc
	v_add_u32_e32 v6, 1, v3
	v_cmp_ge_u32_e32 vcc, v5, v4
	v_add_u32_e32 v5, 1, v7
	s_nop 0
	v_cndmask_b32_e32 v3, v3, v6, vcc
	v_mul_lo_u32 v6, v4, v3
	v_add_u32_e32 v4, v6, v4
	v_cmp_ne_u32_e32 vcc, v5, v4
	s_and_saveexec_b64 s[2:3], vcc
	s_xor_b64 s[12:13], exec, s[2:3]
	s_cbranch_execz .LBB0_293
	s_waitcnt lgkmcnt(0)
	buffer_inv sc1
	s_add_u32 s22, s8, 0xfc9f500
	s_addc_u32 s23, s9, 0
	global_load_dword v2, v199, s[22:23] sc1
	s_waitcnt vmcnt(0)
	v_cmp_eq_u32_e32 vcc, v2, v3
	s_and_saveexec_b64 s[14:15], vcc
	s_cbranch_execz .LBB0_292
	s_add_u32 s18, s8, 0xfc9c200
	s_addc_u32 s19, s9, 0
	s_mov_b32 s2, 1
	s_mov_b64 s[24:25], 0
	s_branch .LBB0_283

; DI unsigned xb_ld(unsigned* p) { return __hip_atomic_load(p, __ATOMIC_RELAXED, __HIP_MEMORY_SCOPE_AGENT); }
; DI unsigned xb_add(unsigned* p, unsigned v) { return __hip_atomic_fetch_add(p, v, __ATOMIC_RELAXED, __HIP_MEMORY_SCOPE_AGENT); }
; #define XB_SPIN(cond, bar) do { unsigned _sp = 0; while (cond) { __builtin_amdgcn_s_sleep(1); \
;     if ((++_sp & 255u) == 0u) { if (xb_ld(&(bar)[XB_TMO])) break; if (_sp > XB_SPIN_CAP) { atomicAdd(&(bar)[XB_TMO], 1u); break; } } } } while (0)
; DI void xcd_barrier(const XcdBarrier& b) {
;     ...
;     const unsigned old = xb_add(&bar[XB_XSUB(b.x)], 1u);
;     const unsigned gen = old / nloc;
;     if (old + 1u == (gen + 1u) * nloc) {
;       __builtin_amdgcn_fence(__ATOMIC_RELEASE, "agent");
;       asm volatile("s_waitcnt vmcnt(0)" ::: "memory");
;       const unsigned og = xb_add(&bar[XB_TOP], 1u);
;       const unsigned tg = og / nx;
;       if (og + 1u == (tg + 1u) * nx) xb_add(&bar[XB_TOPGEN], 1u);
;       else XB_SPIN(xb_ld(&bar[XB_TOPGEN]) == tg, bar);
;       __builtin_amdgcn_fence(__ATOMIC_ACQUIRE, "agent");
;       xb_add(&bar[XB_XGEN(b.x)], 1u);
;       asm volatile("s_waitcnt vmcnt(0)" ::: "memory");
;     } else {
;       XB_SPIN(xb_ld(&bar[XB_XGEN(b.x)]) == gen, bar);
;       __builtin_amdgcn_fence(__ATOMIC_ACQUIRE, "agent");
.LBB0_875:
	s_or_b64 exec, exec, s[14:15]
	v_cvt_f32_u32_e32 v6, v4
	s_waitcnt vmcnt(0)
	v_readfirstlane_b32 s2, v5
	v_sub_u32_e32 v5, 0, v4
	v_rcp_iflag_f32_e32 v6, v6
	v_add_u32_e32 v7, s2, v3
	v_mul_f32_e32 v6, 0x4f7ffffe, v6
	v_cvt_u32_f32_e32 v6, v6
	v_mul_lo_u32 v3, v5, v6
	v_mul_hi_u32 v3, v6, v3
	v_add_u32_e32 v3, v6, v3
	v_mul_hi_u32 v3, v7, v3
	v_mul_lo_u32 v5, v3, v4
	v_sub_u32_e32 v5, v7, v5
	v_add_u32_e32 v6, 1, v3
	v_cmp_ge_u32_e32 vcc, v5, v4
	s_nop 1
	v_cndmask_b32_e32 v3, v3, v6, vcc
	v_sub_u32_e32 v6, v5, v4
	v_cndmask_b32_e32 v5, v5, v6, vcc
	v_add_u32_e32 v6, 1, v3
	v_cmp_ge_u32_e32 vcc, v5, v4
	v_add_u32_e32 v5, 1, v7
	s_nop 0
	v_cndmask_b32_e32 v3, v3, v6, vcc
	v_mul_lo_u32 v6, v4, v3
	v_add_u32_e32 v4, v6, v4
	v_cmp_ne_u32_e32 vcc, v5, v4
	s_and_saveexec_b64 s[2:3], vcc
	s_xor_b64 s[12:13], exec, s[2:3]
	s_cbranch_execz .LBB0_889
	s_waitcnt lgkmcnt(0)
	buffer_inv sc1
	s_add_u32 s18, s8, 0xfc9f500
	s_addc_u32 s19, s9, 0
	global_load_dword v2, v199, s[18:19] sc1
	s_waitcnt vmcnt(0)
	v_cmp_eq_u32_e32 vcc, v2, v3
	s_and_saveexec_b64 s[14:15], vcc
	s_cbranch_execz .LBB0_888
	s_add_u32 s16, s8, 0xfc9c200
	s_addc_u32 s17, s9, 0
	s_mov_b32 s2, 1
	s_mov_b64 s[22:23], 0
	s_branch .LBB0_879

; DI unsigned xb_ld(unsigned* p) { return __hip_atomic_load(p, __ATOMIC_RELAXED, __HIP_MEMORY_SCOPE_AGENT); }
; DI unsigned xb_add(unsigned* p, unsigned v) { return __hip_atomic_fetch_add(p, v, __ATOMIC_RELAXED, __HIP_MEMORY_SCOPE_AGENT); }
; #define XB_SPIN(cond, bar) do { unsigned _sp = 0; while (cond) { __builtin_amdgcn_s_sleep(1); \
;     if ((++_sp & 255u) == 0u) { if (xb_ld(&(bar)[XB_TMO])) break; if (_sp > XB_SPIN_CAP) { atomicAdd(&(bar)[XB_TMO], 1u); break; } } } } while (0)
; DI void xcd_barrier(const XcdBarrier& b) {
;     ...
;     const unsigned old = xb_add(&bar[XB_XSUB(b.x)], 1u);
;     const unsigned gen = old / nloc;
;     if (old + 1u == (gen + 1u) * nloc) {
;       __builtin_amdgcn_fence(__ATOMIC_RELEASE, "agent");
;       asm volatile("s_waitcnt vmcnt(0)" ::: "memory");
;       const unsigned og = xb_add(&bar[XB_TOP], 1u);
;       const unsigned tg = og / nx;
;       if (og + 1u == (tg + 1u) * nx) xb_add(&bar[XB_TOPGEN], 1u);
;       else XB_SPIN(xb_ld(&bar[XB_TOPGEN]) == tg, bar);
;       __builtin_amdgcn_fence(__ATOMIC_ACQUIRE, "agent");
;       xb_add(&bar[XB_XGEN(b.x)], 1u);
;       asm volatile("s_waitcnt vmcnt(0)" ::: "memory");
;     } else {
;       XB_SPIN(xb_ld(&bar[XB_XGEN(b.x)]) == gen, bar);
;       __builtin_amdgcn_fence(__ATOMIC_ACQUIRE, "agent");
.LBB0_1819:
	s_or_b64 exec, exec, s[18:19]
	v_cvt_f32_u32_e32 v6, v4
	s_waitcnt vmcnt(0)
	v_readfirstlane_b32 s2, v5
	v_sub_u32_e32 v5, 0, v4
	v_rcp_iflag_f32_e32 v6, v6
	v_add_u32_e32 v7, s2, v3
	v_mul_f32_e32 v6, 0x4f7ffffe, v6
	v_cvt_u32_f32_e32 v6, v6
	v_mul_lo_u32 v3, v5, v6
	v_mul_hi_u32 v3, v6, v3
	v_add_u32_e32 v3, v6, v3
	v_mul_hi_u32 v3, v7, v3
	v_mul_lo_u32 v5, v3, v4
	v_sub_u32_e32 v5, v7, v5
	v_add_u32_e32 v6, 1, v3
	v_cmp_ge_u32_e32 vcc, v5, v4
	s_nop 1
	v_cndmask_b32_e32 v3, v3, v6, vcc
	v_sub_u32_e32 v6, v5, v4
	v_cndmask_b32_e32 v5, v5, v6, vcc
	v_add_u32_e32 v6, 1, v3
	v_cmp_ge_u32_e32 vcc, v5, v4
	v_add_u32_e32 v5, 1, v7
	s_nop 0
	v_cndmask_b32_e32 v3, v3, v6, vcc
	v_mul_lo_u32 v6, v4, v3
	v_add_u32_e32 v4, v6, v4
	v_cmp_ne_u32_e32 vcc, v5, v4
	s_and_saveexec_b64 s[2:3], vcc
	s_xor_b64 s[16:17], exec, s[2:3]
	s_cbranch_execz .LBB0_1833
	s_waitcnt lgkmcnt(0)
	buffer_inv sc1
	s_add_u32 s24, s12, 0xfc9f500
	s_addc_u32 s25, s13, 0
	global_load_dword v2, v199, s[24:25] sc1
	s_waitcnt vmcnt(0)
	v_cmp_eq_u32_e32 vcc, v2, v3
	s_and_saveexec_b64 s[18:19], vcc
	s_cbranch_execz .LBB0_1832
	s_add_u32 s22, s12, 0xfc9c200
	s_addc_u32 s23, s13, 0
	s_mov_b32 s2, 1
	s_mov_b64 s[26:27], 0
	s_branch .LBB0_1823
